# speedup vs baseline: 1.0062x; 1.0007x over previous
; __device__ __forceinline__ const float* inp(const Params& p, int i) { auto g = (__attribute__((address_space(1))) const float*)p.in[i]; asm volatile("" : "+s"(g)); return (const float*)g; }
; __device__ __forceinline__ void attn_phase(const Params& p, int j, u16* Q, const u16* K, const u16* Vt) {
;     ...
;   const float* qg = inp(p, 26) + j * 64;
;   const float* kg = inp(p, 27) + j * 64;
;   const float* rpb = inp(p, 28) + (size_t)j * 16 * 15 * 31;
;   for (int i_ = tid_; i_ < 16 * 15 * 31; i_ += NTHREADS) RPB[i_] = rpb[i_];
;   float qgs[2][8];
;   _Pragma("unroll") for (int ks = 0; ks < 2; ++ks) _Pragma("unroll") for (int e = 0; e < 8; ++e) {
;     qgs[ks][e] = qg[ks * 32 + fq * 8 + e] * 0.125f * kg[ks * 32 + fq * 8 + e]; }
;   __syncthreads();
;   for (int it = blockIdx.x; it < 768 * 16; it += gridDim.x) {
;     int h = it & 15, rp = it >> 4;
;     int grow = rp * 2 + (wv >> 2), cb = wv & 3;
;     int rows, seqrow0;
;     if (grow < 1024) { rows = 32; seqrow0 = grow & ~31; } else { rows = 128; seqrow0 = 1024 + ((grow - 1024) & ~127); }
;     int i = grow - seqrow0;
;     int r0 = min(max(i - 4, 0), rows - 8);
;     int sstart = min(max(cb * 16 - 8, 0), 32);
;     unsigned qoff = ((unsigned)(grow * 64 + cb * 16 + fr) * 1024u + (unsigned)(h * 64 + fq * 8)) * 2u;
;     unsigned koff0 = ((unsigned)((seqrow0 + r0) * 64 + sstart + fr) * 1024u + (unsigned)(h * 64 + fq * 8)) * 2u;
.LBB0_453:
	s_or_b64 exec, exec, s[6:7]
	v_readlane_b32 s2, v246, 26
	v_readlane_b32 s3, v246, 27
	v_readlane_b32 s8, v247, 14
	s_lshl_b32 s2, s2, 6
	s_mov_b32 s3, s8
	s_lshl_b64 s[2:3], s[2:3], 2
	s_add_u32 s4, s4, s2
	v_bfe_u32 v33, v32, 4, 2
	s_addc_u32 s5, s5, s3
	s_add_u32 s0, s0, s2
	v_lshlrev_b32_e32 v12, 5, v33
	s_addc_u32 s1, s1, s3
	global_load_dwordx4 v[16:19], v12, s[4:5] offset:16
	global_load_dwordx4 v[24:27], v12, s[4:5]
	global_load_dwordx4 v[20:23], v12, s[0:1] offset:16
	global_load_dwordx4 v[28:31], v12, s[0:1]
	global_load_dwordx4 v[0:3], v12, s[4:5] offset:144
	global_load_dwordx4 v[8:11], v12, s[4:5] offset:128
	global_load_dwordx4 v[4:7], v12, s[0:1] offset:144
	s_nop 0
	global_load_dwordx4 v[12:15], v12, s[0:1] offset:128
	v_readlane_b32 s0, v247, 30
	v_readlane_b32 s1, v247, 31
	s_and_b64 vcc, exec, s[0:1]
	v_readlane_b32 s9, v247, 15
	v_readlane_b32 s10, v247, 16
	v_readlane_b32 s11, v247, 17
	s_waitcnt lgkmcnt(0)
	s_barrier
	s_cbranch_vccz .LBB0_584
	s_mov_b32 s0, 0x3e000000
	s_waitcnt vmcnt(3)
	v_pk_mul_f32 v[0:1], v[0:1], s[0:1] op_sel_hi:[1,0]
	v_pk_mul_f32 v[24:25], v[24:25], s[0:1] op_sel_hi:[1,0]
	v_pk_mul_f32 v[16:17], v[16:17], s[0:1] op_sel_hi:[1,0]
	s_waitcnt vmcnt(2)
	v_pk_mul_f32 v[8:9], v[8:9], s[0:1] op_sel_hi:[1,0]
	s_waitcnt vmcnt(1)
	v_pk_mul_f32 v[108:109], v[0:1], v[4:5]
	v_pk_mul_f32 v[0:1], v[2:3], s[0:1] op_sel_hi:[1,0]
	v_pk_mul_f32 v[96:97], v[24:25], v[28:29]
	v_pk_mul_f32 v[24:25], v[26:27], s[0:1] op_sel_hi:[1,0]
	v_pk_mul_f32 v[100:101], v[16:17], v[20:21]
	v_pk_mul_f32 v[16:17], v[18:19], s[0:1] op_sel_hi:[1,0]
	s_waitcnt vmcnt(0)
	v_pk_mul_f32 v[104:105], v[8:9], v[12:13]
	v_pk_mul_f32 v[8:9], v[10:11], s[0:1] op_sel_hi:[1,0]
	v_pk_mul_f32 v[110:111], v[0:1], v[6:7]
	v_ashrrev_i32_e32 v0, 6, v32
	s_movk_i32 s0, 0x2100
	v_mul_lo_u32 v1, v0, s0
	v_lshlrev_b32_e32 v0, 4, v0
	v_and_b32_e32 v114, 48, v0
	v_sub_u32_e64 v0, v114, 8 clamp
	v_and_b32_e32 v34, 63, v32
	v_and_b32_e32 v112, 15, v32
	v_min_u32_e32 v0, 32, v0
	v_and_b32_e32 v115, 48, v32
	v_add_u32_e32 v2, v0, v112
	v_lshl_add_u32 v116, v0, 1, v115
	v_lshlrev_b32_e32 v0, 2, v34
	v_lshlrev_b32_e32 v119, 2, v33
	v_xor_b32_e32 v117, 64, v0
	v_xor_b32_e32 v118, 0x80, v0
	v_or_b32_e32 v0, v119, v114
	v_sub_u32_e32 v5, v2, v0
	v_max_i32_e32 v5, -15, v5
	v_add_u32_e32 v5, 15, v5
	v_min_u32_e32 v120, 30, v5
	v_or_b32_e32 v5, 1, v0
	v_pk_mul_f32 v[106:107], v[8:9], v[14:15]
	v_sub_u32_e32 v8, v2, v5
	v_max_i32_e32 v8, -15, v8
	v_add_u32_e32 v8, 15, v8
	v_min_u32_e32 v121, 30, v8
	v_or_b32_e32 v8, 2, v0
	v_sub_u32_e32 v11, v2, v8
	v_max_i32_e32 v11, -15, v11
	v_add_u32_e32 v11, 15, v11
	v_min_u32_e32 v122, 30, v11
	v_or_b32_e32 v11, 3, v0
	v_sub_u32_e32 v14, v2, v11
	v_max_i32_e32 v14, -15, v14
	v_add_u32_e32 v14, 15, v14
	v_min_u32_e32 v123, 30, v14
	v_add_u32_e32 v14, 16, v2
	v_sub_u32_e64 v3, v0, 8 clamp
	v_sub_u32_e32 v0, v14, v0
	v_max_i32_e32 v0, -15, v0
	v_add_u32_e32 v0, 15, v0
	v_min_u32_e32 v124, 30, v0
	v_sub_u32_e32 v0, v14, v5
	v_max_i32_e32 v0, -15, v0
	v_min_u32_e32 v3, 48, v3
	v_sub_u32_e64 v6, v5, 8 clamp
	v_add_u32_e32 v0, 15, v0
	v_add_u32_e32 v4, 16, v3
	v_min_u32_e32 v6, 48, v6
	v_sub_u32_e64 v9, v8, 8 clamp
	v_min_u32_e32 v125, 30, v0
	v_sub_u32_e32 v0, v14, v8
	v_cmp_ge_u32_e32 vcc, v2, v3
	v_cmp_lt_u32_e64 s[0:1], v2, v4
	v_add_u32_e32 v7, 16, v6
	v_min_u32_e32 v9, 48, v9
	v_sub_u32_e64 v12, v11, 8 clamp
	v_max_i32_e32 v0, -15, v0
	s_and_b64 s[4:5], vcc, s[0:1]
	v_cmp_ge_u32_e32 vcc, v2, v6
	v_cmp_lt_u32_e64 s[0:1], v2, v7
	v_add_u32_e32 v10, 16, v9
	v_min_u32_e32 v12, 48, v12
	v_add_u32_e32 v0, 15, v0
	s_and_b64 s[6:7], vcc, s[0:1]
	v_cmp_ge_u32_e32 vcc, v2, v9
	v_cmp_lt_u32_e64 s[0:1], v2, v10
	v_add_u32_e32 v13, 16, v12
	v_min_u32_e32 v126, 30, v0
	v_sub_u32_e32 v0, v14, v11
	s_and_b64 s[8:9], vcc, s[0:1]
	v_cmp_ge_u32_e32 vcc, v2, v12
	v_cmp_lt_u32_e64 s[0:1], v2, v13
	v_max_i32_e32 v0, -15, v0
	s_and_b64 s[10:11], vcc, s[0:1]
	v_cmp_ge_u32_e32 vcc, v14, v3
	v_cmp_lt_u32_e64 s[0:1], v14, v4
	v_add_u32_e32 v0, 15, v0
	s_and_b64 s[12:13], vcc, s[0:1]
	v_cmp_ge_u32_e32 vcc, v14, v6
	v_cmp_lt_u32_e64 s[0:1], v14, v7
	v_min_u32_e32 v127, 30, v0
	v_mul_u32_u24_e32 v0, 0x210, v112
	s_and_b64 s[14:15], vcc, s[0:1]
	v_cmp_ge_u32_e32 vcc, v14, v9
	v_cmp_lt_u32_e64 s[0:1], v14, v10
	v_add3_u32 v0, 0, v1, v0
	v_mul_u32_u24_e32 v1, 0x420, v33
	v_lshlrev_b32_e32 v35, 3, v33
	s_and_b64 s[16:17], vcc, s[0:1]
	v_cmp_ge_u32_e32 vcc, v14, v12
	v_cmp_lt_u32_e64 s[0:1], v14, v13
	v_lshlrev_b32_e32 v132, 11, v2
	v_mul_i32_i24_e32 v2, 0xfffffdf2, v112
	v_lshlrev_b32_e32 v1, 1, v1
	v_pk_mul_f32 v[98:99], v[24:25], v[30:31]
	v_pk_mul_f32 v[102:103], v[16:17], v[22:23]
	v_ashrrev_i32_e32 v113, 8, v32
	s_and_b64 s[0:1], vcc, s[0:1]
	v_lshl_add_u32 v128, v35, 1, v0
	v_add3_u32 v133, v0, v2, v1
	s_add_i32 s2, s92, 0x2f00
	s_branch .LBB0_456
; __device__ __forceinline__ void attn_phase(const Params& p, int j, u16* Q, const u16* K, const u16* Vt) {
;     ...
;     auto load_v = [&](int bt, bf16x8 (&vf)[2][4]) {
;       _Pragma("unroll") for (int k2 = 0; k2 < 2; ++k2) _Pragma("unroll") for (int nd = 0; nd < 4; ++nd)
;         vf[k2][nd] = ldo<bf16x8>(Vt, voff0 + (unsigned)((bt * 2 + k2) * 16 * 64 * 64 + nd * 16 * 64) * 2u);
;     };
;     ...
;     float inv[4];
;     _Pragma("unroll") for (int jj = 0; jj < 4; ++jj) {
;       float m = -1e30f;
;       _Pragma("unroll") for (int t = 0; t < 16; ++t) m = fmaxf(m, sc[t][jj]);
;       m = row_max(m);
;       float s_ = 0.f;
;       _Pragma("unroll") for (int t = 0; t < 16; ++t) { float e = __expf(sc[t][jj] - m); sc[t][jj] = e; s_ += e; }
;       s_ = row_sum(s_);
;       inv[jj] = 1.f / s_;
;     }
;     _Pragma("unroll") for (int t = 0; t < 16; ++t) _Pragma("unroll") for (int jj = 0; jj < 4; ++jj)
;       P[(fq * 4 + jj) * 264 + t * 16 + fr] = f2b(sc[t][jj]);
.LBB0_455:
	s_or_b64 exec, exec, s[18:19]
	s_mov_b32 s28, 0xf149f2ca
	v_max3_f32 v70, v147, s28, v151
	v_max3_f32 v70, v70, v155, v160
	v_max3_f32 v70, v70, v163, v165
	v_max3_f32 v70, v70, v167, v169
	v_max3_f32 v70, v70, v92, v94
	v_max3_f32 v70, v70, v168, v172
	v_max3_f32 v70, v70, v159, v64
	v_max3_f32 v70, v70, v156, v176
	v_add_u32_e32 v0, 0x40000, v72
	v_add_u32_e32 v40, 0x41000, v72
	v_mov_b32_dpp v71, v70 quad_perm:[1,0,3,2] row_mask:0xf bank_mask:0xf bound_ctrl:1
	v_max_f32_e32 v71, v71, v71
	v_max_f32_e32 v70, v70, v71
	global_load_dwordx4 v[0:3], v0, s[30:31]
	v_add_u32_e32 v4, 0x40800, v72
	v_mov_b32_dpp v71, v70 quad_perm:[2,3,0,1] row_mask:0xf bank_mask:0xf bound_ctrl:1
	v_max_f32_e32 v71, v71, v71
	v_max_f32_e32 v70, v70, v71
	global_load_dwordx4 v[40:43], v40, s[30:31]
	v_add_u32_e32 v44, 0x41800, v72
	v_mov_b32_dpp v71, v70 row_half_mirror row_mask:0xf bank_mask:0xf bound_ctrl:1
	v_max_f32_e32 v71, v71, v71
	v_max_f32_e32 v70, v70, v71
	global_load_dwordx4 v[4:7], v4, s[30:31]
	v_add_u32_e32 v48, 0x60000, v72
	v_mov_b32_dpp v71, v70 row_ror:8 row_mask:0xf bank_mask:0xf bound_ctrl:1
	v_max_f32_e32 v71, v71, v71
	v_max_f32_e32 v177, v70, v71
	v_sub_f32_e32 v70, v147, v177
	v_mul_f32_e32 v70, 0x3fb8aa3b, v70
	v_sub_f32_e32 v71, v151, v177
	v_exp_f32_e32 v70, v70
	v_mul_f32_e32 v71, 0x3fb8aa3b, v71
	v_exp_f32_e32 v71, v71
	v_sub_f32_e32 v64, v64, v177
	v_add_f32_e32 v81, 0, v70
	v_mul_f32_e32 v64, 0x3fb8aa3b, v64
	v_add_f32_e32 v82, v71, v81
	v_sub_f32_e32 v81, v155, v177
	v_mul_f32_e32 v81, 0x3fb8aa3b, v81
	v_exp_f32_e32 v81, v81
	v_sub_f32_e32 v156, v156, v177
	v_mul_f32_e32 v156, 0x3fb8aa3b, v156
	v_exp_f32_e32 v156, v156
	v_add_f32_e32 v83, v81, v82
	v_sub_f32_e32 v82, v160, v177
	v_mul_f32_e32 v82, 0x3fb8aa3b, v82
	v_exp_f32_e32 v82, v82
	v_cvt_pk_bf16_f32 v70, v70, s0
	ds_write_b16 v133, v70
	global_load_dwordx4 v[44:47], v44, s[30:31]
	v_add_f32_e32 v84, v82, v83
	v_sub_f32_e32 v83, v163, v177
	v_mul_f32_e32 v83, 0x3fb8aa3b, v83
	v_exp_f32_e32 v83, v83
	global_load_dwordx4 v[48:51], v48, s[30:31]
	v_add_u32_e32 v52, 0x60800, v72
	global_load_dwordx4 v[52:55], v52, s[30:31]
	v_add_f32_e32 v85, v83, v84
	v_sub_f32_e32 v84, v165, v177
	v_mul_f32_e32 v84, 0x3fb8aa3b, v84
	v_exp_f32_e32 v84, v84
	v_add_u32_e32 v56, 0x61000, v72
	global_load_dwordx4 v[56:59], v56, s[30:31]
	v_add_u32_e32 v60, 0x61800, v72
	v_add_f32_e32 v86, v84, v85
	v_sub_f32_e32 v85, v167, v177
	v_mul_f32_e32 v85, 0x3fb8aa3b, v85
	v_exp_f32_e32 v85, v85
	global_load_dwordx4 v[60:63], v60, s[30:31]
	s_sub_i32 s2, s2, s81
	s_cmp_gt_i32 s2, -1
	v_add_f32_e32 v87, v85, v86
	v_sub_f32_e32 v86, v169, v177
	v_mul_f32_e32 v86, 0x3fb8aa3b, v86
	v_exp_f32_e32 v86, v86
	s_nop 0
	v_add_f32_e32 v147, v86, v87
	v_sub_f32_e32 v87, v92, v177
	v_mul_f32_e32 v87, 0x3fb8aa3b, v87
	v_sub_f32_e32 v92, v94, v177
	v_exp_f32_e32 v87, v87
	v_mul_f32_e32 v92, 0x3fb8aa3b, v92
	v_sub_f32_e32 v94, v168, v177
	v_exp_f32_e32 v92, v92
	v_mul_f32_e32 v94, 0x3fb8aa3b, v94
	v_exp_f32_e32 v94, v94
	v_add_f32_e32 v147, v87, v147
	v_add_f32_e32 v147, v92, v147
	v_add_f32_e32 v151, v94, v147
	v_sub_f32_e32 v147, v172, v177
	v_mul_f32_e32 v147, 0x3fb8aa3b, v147
	v_exp_f32_e32 v147, v147
	s_nop 0
	v_add_f32_e32 v155, v147, v151
	v_sub_f32_e32 v151, v159, v177
	v_mul_f32_e32 v151, 0x3fb8aa3b, v151
	v_exp_f32_e32 v151, v151
	s_nop 0
	v_add_f32_e32 v159, v151, v155
	v_exp_f32_e32 v155, v64
	s_nop 0
	v_add_f32_e32 v64, v155, v159
	v_sub_f32_e32 v159, v176, v177
	v_mul_f32_e32 v159, 0x3fb8aa3b, v159
	v_exp_f32_e32 v159, v159
	v_add_f32_e32 v64, v156, v64
	v_add_f32_e32 v64, v159, v64
	s_nop 1
	v_add_f32_dpp v64, v64, v64 quad_perm:[1,0,3,2] row_mask:0xf bank_mask:0xf bound_ctrl:1
	s_nop 1
	v_add_f32_dpp v64, v64, v64 quad_perm:[2,3,0,1] row_mask:0xf bank_mask:0xf bound_ctrl:1
	s_nop 1
	v_add_f32_dpp v64, v64, v64 row_half_mirror row_mask:0xf bank_mask:0xf bound_ctrl:1
	s_nop 1
	v_add_f32_dpp v64, v64, v64 row_ror:8 row_mask:0xf bank_mask:0xf bound_ctrl:1
	v_div_scale_f32 v160, s[18:19], v64, v64, 1.0
	v_rcp_f32_e32 v163, v160
	s_nop 0
	v_fma_f32 v165, -v160, v163, 1.0
	v_fmac_f32_e32 v163, v165, v163
	v_div_scale_f32 v165, vcc, 1.0, v64, 1.0
	v_mul_f32_e32 v167, v165, v163
	v_fma_f32 v168, -v160, v167, v165
	v_fmac_f32_e32 v167, v168, v163
	v_fma_f32 v160, -v160, v167, v165
	v_div_fmas_f32 v160, v160, v163, v167
	v_div_fixup_f32 v64, v160, v64, 1.0
	v_max3_f32 v160, v141, s28, v144
	v_max3_f32 v160, v160, v148, v152
	v_max3_f32 v160, v160, v157, v161
	v_max3_f32 v160, v160, v164, v166
	v_max3_f32 v160, v160, v90, v79
	v_max3_f32 v160, v160, v93, v95
	v_max3_f32 v160, v160, v170, v65
	v_max3_f32 v160, v160, v174, v175
	s_nop 1
	v_mov_b32_dpp v163, v160 quad_perm:[1,0,3,2] row_mask:0xf bank_mask:0xf bound_ctrl:1
	v_max_f32_e32 v163, v163, v163
	v_max_f32_e32 v160, v160, v163
	s_nop 1
	v_mov_b32_dpp v163, v160 quad_perm:[2,3,0,1] row_mask:0xf bank_mask:0xf bound_ctrl:1
	v_max_f32_e32 v163, v163, v163
	v_max_f32_e32 v160, v160, v163
	s_nop 1
	v_mov_b32_dpp v163, v160 row_half_mirror row_mask:0xf bank_mask:0xf bound_ctrl:1
	v_max_f32_e32 v163, v163, v163
	v_max_f32_e32 v160, v160, v163
	s_nop 1
	v_mov_b32_dpp v163, v160 row_ror:8 row_mask:0xf bank_mask:0xf bound_ctrl:1
	v_max_f32_e32 v163, v163, v163
	v_max_f32_e32 v167, v160, v163
	v_sub_f32_e32 v141, v141, v167
	v_mul_f32_e32 v141, 0x3fb8aa3b, v141
	v_sub_f32_e32 v144, v144, v167
	v_exp_f32_e32 v141, v141
	v_mul_f32_e32 v144, 0x3fb8aa3b, v144
	v_sub_f32_e32 v148, v148, v167
	v_exp_f32_e32 v144, v144
	v_mul_f32_e32 v148, 0x3fb8aa3b, v148
	v_sub_f32_e32 v152, v152, v167
	v_exp_f32_e32 v148, v148
	v_mul_f32_e32 v152, 0x3fb8aa3b, v152
; __device__ __forceinline__ void attn_phase(const Params& p, int j, u16* Q, const u16* K, const u16* Vt) {
;     ...
;     float inv[4];
;     _Pragma("unroll") for (int jj = 0; jj < 4; ++jj) {
;       float m = -1e30f;
;       _Pragma("unroll") for (int t = 0; t < 16; ++t) m = fmaxf(m, sc[t][jj]);
;       m = row_max(m);
;       float s_ = 0.f;
;       _Pragma("unroll") for (int t = 0; t < 16; ++t) { float e = __expf(sc[t][jj] - m); sc[t][jj] = e; s_ += e; }
;       s_ = row_sum(s_);
;       inv[jj] = 1.f / s_;
;     }
;     _Pragma("unroll") for (int t = 0; t < 16; ++t) _Pragma("unroll") for (int jj = 0; jj < 4; ++jj)
;       P[(fq * 4 + jj) * 264 + t * 16 + fr] = f2b(sc[t][jj]);
	v_sub_f32_e32 v157, v157, v167
	v_exp_f32_e32 v152, v152
	v_mul_f32_e32 v157, 0x3fb8aa3b, v157
	v_add_f32_e32 v160, 0, v141
	v_exp_f32_e32 v157, v157
	v_add_f32_e32 v160, v144, v160
	v_add_f32_e32 v160, v148, v160
	v_add_f32_e32 v160, v152, v160
	v_add_f32_e32 v163, v157, v160
	v_sub_f32_e32 v160, v161, v167
	v_mul_f32_e32 v160, 0x3fb8aa3b, v160
	v_sub_f32_e32 v161, v164, v167
	v_exp_f32_e32 v160, v160
	v_mul_f32_e32 v161, 0x3fb8aa3b, v161
	v_exp_f32_e32 v161, v161
	v_sub_f32_e32 v90, v90, v167
	v_add_f32_e32 v163, v160, v163
	v_mul_f32_e32 v90, 0x3fb8aa3b, v90
	v_add_f32_e32 v164, v161, v163
	v_sub_f32_e32 v163, v166, v167
	v_mul_f32_e32 v163, 0x3fb8aa3b, v163
	v_exp_f32_e32 v163, v163
	v_sub_f32_e32 v79, v79, v167
	v_exp_f32_e32 v90, v90
	v_mul_f32_e32 v79, 0x3fb8aa3b, v79
	v_sub_f32_e32 v93, v93, v167
	v_exp_f32_e32 v79, v79
	v_mul_f32_e32 v93, 0x3fb8aa3b, v93
	v_sub_f32_e32 v95, v95, v167
	v_exp_f32_e32 v93, v93
	v_mul_f32_e32 v95, 0x3fb8aa3b, v95
	v_add_f32_e32 v164, v163, v164
	v_exp_f32_e32 v95, v95
	v_add_f32_e32 v164, v90, v164
	v_add_f32_e32 v164, v79, v164
	v_add_f32_e32 v164, v93, v164
	v_add_f32_e32 v165, v95, v164
	v_sub_f32_e32 v164, v170, v167
	v_mul_f32_e32 v164, 0x3fb8aa3b, v164
	v_exp_f32_e32 v164, v164
	v_sub_f32_e32 v65, v65, v167
	v_mul_f32_e32 v65, 0x3fb8aa3b, v65
	v_cvt_pk_bf16_f32 v70, v141, s0
	v_add_f32_e32 v166, v164, v165
	v_exp_f32_e32 v165, v65
	ds_write_b16 v133, v70 offset:528
	v_add_f32_e32 v65, v165, v166
	v_sub_f32_e32 v166, v174, v167
	v_mul_f32_e32 v166, 0x3fb8aa3b, v166
	v_sub_f32_e32 v167, v175, v167
	v_exp_f32_e32 v166, v166
	v_mul_f32_e32 v167, 0x3fb8aa3b, v167
	v_exp_f32_e32 v167, v167
	v_add_f32_e32 v65, v166, v65
	v_add_f32_e32 v65, v167, v65
	s_nop 1
	v_add_f32_dpp v65, v65, v65 quad_perm:[1,0,3,2] row_mask:0xf bank_mask:0xf bound_ctrl:1
	s_nop 1
	v_add_f32_dpp v65, v65, v65 quad_perm:[2,3,0,1] row_mask:0xf bank_mask:0xf bound_ctrl:1
	s_nop 1
	v_add_f32_dpp v65, v65, v65 row_half_mirror row_mask:0xf bank_mask:0xf bound_ctrl:1
	s_nop 1
	v_add_f32_dpp v65, v65, v65 row_ror:8 row_mask:0xf bank_mask:0xf bound_ctrl:1
	v_div_scale_f32 v168, s[18:19], v65, v65, 1.0
	v_rcp_f32_e32 v169, v168
	s_nop 0
	v_fma_f32 v170, -v168, v169, 1.0
	v_fmac_f32_e32 v169, v170, v169
	v_div_scale_f32 v170, vcc, 1.0, v65, 1.0
	v_mul_f32_e32 v172, v170, v169
	v_fma_f32 v174, -v168, v172, v170
	v_fmac_f32_e32 v172, v174, v169
	v_fma_f32 v168, -v168, v172, v170
	v_div_fmas_f32 v168, v168, v169, v172
	v_div_fixup_f32 v65, v168, v65, 1.0
	v_max3_f32 v168, v137, s28, v139
	v_max3_f32 v168, v168, v142, v145
	v_max3_f32 v168, v168, v149, v153
	v_max3_f32 v168, v168, v158, v162
	v_max3_f32 v168, v168, v89, v75
	v_max3_f32 v168, v168, v77, v91
	v_max3_f32 v168, v168, v80, v67
	v_max3_f32 v168, v168, v171, v173
	s_nop 1
	v_mov_b32_dpp v169, v168 quad_perm:[1,0,3,2] row_mask:0xf bank_mask:0xf bound_ctrl:1
	v_max_f32_e32 v169, v169, v169
	v_max_f32_e32 v168, v168, v169
	s_nop 1
	v_mov_b32_dpp v169, v168 quad_perm:[2,3,0,1] row_mask:0xf bank_mask:0xf bound_ctrl:1
	v_max_f32_e32 v169, v169, v169
	v_max_f32_e32 v168, v168, v169
	s_nop 1
	v_mov_b32_dpp v169, v168 row_half_mirror row_mask:0xf bank_mask:0xf bound_ctrl:1
	v_max_f32_e32 v169, v169, v169
	v_max_f32_e32 v168, v168, v169
	s_nop 1
	v_mov_b32_dpp v169, v168 row_ror:8 row_mask:0xf bank_mask:0xf bound_ctrl:1
	v_max_f32_e32 v169, v169, v169
	v_max_f32_e32 v168, v168, v169
	v_sub_f32_e32 v137, v137, v168
	v_mul_f32_e32 v137, 0x3fb8aa3b, v137
	v_sub_f32_e32 v139, v139, v168
	v_exp_f32_e32 v137, v137
	v_mul_f32_e32 v139, 0x3fb8aa3b, v139
	v_sub_f32_e32 v142, v142, v168
	v_exp_f32_e32 v139, v139
	v_mul_f32_e32 v142, 0x3fb8aa3b, v142
	v_sub_f32_e32 v145, v145, v168
	v_exp_f32_e32 v142, v142
	v_mul_f32_e32 v145, 0x3fb8aa3b, v145
	v_sub_f32_e32 v149, v149, v168
	v_exp_f32_e32 v145, v145
	v_mul_f32_e32 v149, 0x3fb8aa3b, v149
	v_sub_f32_e32 v153, v153, v168
	v_add_f32_e32 v169, 0, v137
	v_exp_f32_e32 v149, v149
	v_mul_f32_e32 v153, 0x3fb8aa3b, v153
	v_sub_f32_e32 v158, v158, v168
	v_add_f32_e32 v169, v139, v169
	v_exp_f32_e32 v153, v153
	v_mul_f32_e32 v158, 0x3fb8aa3b, v158
	v_sub_f32_e32 v162, v162, v168
	v_add_f32_e32 v169, v142, v169
	v_exp_f32_e32 v158, v158
	v_mul_f32_e32 v162, 0x3fb8aa3b, v162
	v_sub_f32_e32 v89, v89, v168
	v_add_f32_e32 v169, v145, v169
	v_exp_f32_e32 v162, v162
	v_mul_f32_e32 v89, 0x3fb8aa3b, v89
	v_sub_f32_e32 v75, v75, v168
	v_add_f32_e32 v169, v149, v169
	v_exp_f32_e32 v89, v89
	v_mul_f32_e32 v75, 0x3fb8aa3b, v75
	v_sub_f32_e32 v77, v77, v168
	v_add_f32_e32 v169, v153, v169
	v_exp_f32_e32 v75, v75
	v_mul_f32_e32 v77, 0x3fb8aa3b, v77
	v_sub_f32_e32 v91, v91, v168
	v_add_f32_e32 v169, v158, v169
	v_exp_f32_e32 v77, v77
	v_mul_f32_e32 v91, 0x3fb8aa3b, v91
	v_sub_f32_e32 v80, v80, v168
	v_add_f32_e32 v169, v162, v169
	v_exp_f32_e32 v91, v91
	v_mul_f32_e32 v80, 0x3fb8aa3b, v80
	v_sub_f32_e32 v67, v67, v168
	v_add_f32_e32 v169, v89, v169
	v_exp_f32_e32 v80, v80
	v_mul_f32_e32 v67, 0x3fb8aa3b, v67
	v_add_f32_e32 v169, v75, v169
	v_exp_f32_e32 v170, v67
	v_add_f32_e32 v169, v77, v169
	v_add_f32_e32 v169, v91, v169
	v_add_f32_e32 v169, v80, v169
	v_add_f32_e32 v67, v170, v169
	v_sub_f32_e32 v169, v171, v168
	v_mul_f32_e32 v169, 0x3fb8aa3b, v169
	v_sub_f32_e32 v168, v173, v168
	v_exp_f32_e32 v169, v169
	v_mul_f32_e32 v168, 0x3fb8aa3b, v168
	v_exp_f32_e32 v168, v168
	v_cvt_pk_bf16_f32 v70, v137, s0
	v_add_f32_e32 v67, v169, v67
	ds_write_b16 v133, v70 offset:1056
	v_add_f32_e32 v67, v168, v67
	s_nop 1
	v_add_f32_dpp v67, v67, v67 quad_perm:[1,0,3,2] row_mask:0xf bank_mask:0xf bound_ctrl:1
	s_nop 1
	v_add_f32_dpp v67, v67, v67 quad_perm:[2,3,0,1] row_mask:0xf bank_mask:0xf bound_ctrl:1
; __device__ __forceinline__ void attn_phase(const Params& p, int j, u16* Q, const u16* K, const u16* Vt) {
;     ...
;     float inv[4];
;     _Pragma("unroll") for (int jj = 0; jj < 4; ++jj) {
;       float m = -1e30f;
;       _Pragma("unroll") for (int t = 0; t < 16; ++t) m = fmaxf(m, sc[t][jj]);
;       m = row_max(m);
;       float s_ = 0.f;
;       _Pragma("unroll") for (int t = 0; t < 16; ++t) { float e = __expf(sc[t][jj] - m); sc[t][jj] = e; s_ += e; }
;       s_ = row_sum(s_);
;       inv[jj] = 1.f / s_;
;     }
;     _Pragma("unroll") for (int t = 0; t < 16; ++t) _Pragma("unroll") for (int jj = 0; jj < 4; ++jj)
;       P[(fq * 4 + jj) * 264 + t * 16 + fr] = f2b(sc[t][jj]);
	s_nop 1
	v_add_f32_dpp v67, v67, v67 row_half_mirror row_mask:0xf bank_mask:0xf bound_ctrl:1
	s_nop 1
	v_add_f32_dpp v67, v67, v67 row_ror:8 row_mask:0xf bank_mask:0xf bound_ctrl:1
	v_div_scale_f32 v171, s[18:19], v67, v67, 1.0
	v_rcp_f32_e32 v172, v171
	s_nop 0
	v_fma_f32 v173, -v171, v172, 1.0
	v_fmac_f32_e32 v172, v173, v172
	v_div_scale_f32 v173, vcc, 1.0, v67, 1.0
	v_mul_f32_e32 v174, v173, v172
	v_fma_f32 v175, -v171, v174, v173
	v_fmac_f32_e32 v174, v175, v172
	v_fma_f32 v171, -v171, v174, v173
	v_div_fmas_f32 v171, v171, v172, v174
	v_div_fixup_f32 v67, v171, v67, 1.0
	v_max3_f32 v171, v135, s28, v136
	v_max3_f32 v171, v171, v138, v140
	v_max3_f32 v171, v171, v143, v146
	v_max3_f32 v171, v171, v150, v154
	v_max3_f32 v171, v171, v88, v73
	v_max3_f32 v171, v171, v74, v76
	v_max3_f32 v171, v171, v78, v66
	v_max3_f32 v171, v171, v68, v69
	s_nop 1
	v_mov_b32_dpp v172, v171 quad_perm:[1,0,3,2] row_mask:0xf bank_mask:0xf bound_ctrl:1
	v_max_f32_e32 v172, v172, v172
	v_max_f32_e32 v171, v171, v172
	s_nop 1
	v_mov_b32_dpp v172, v171 quad_perm:[2,3,0,1] row_mask:0xf bank_mask:0xf bound_ctrl:1
	v_max_f32_e32 v172, v172, v172
	v_max_f32_e32 v171, v171, v172
	s_nop 1
	v_mov_b32_dpp v172, v171 row_half_mirror row_mask:0xf bank_mask:0xf bound_ctrl:1
	v_max_f32_e32 v172, v172, v172
	v_max_f32_e32 v171, v171, v172
	s_nop 1
	v_mov_b32_dpp v172, v171 row_ror:8 row_mask:0xf bank_mask:0xf bound_ctrl:1
	v_max_f32_e32 v172, v172, v172
	v_max_f32_e32 v171, v171, v172
	v_sub_f32_e32 v135, v135, v171
	v_mul_f32_e32 v135, 0x3fb8aa3b, v135
	v_exp_f32_e32 v135, v135
	v_sub_f32_e32 v136, v136, v171
	v_mul_f32_e32 v136, 0x3fb8aa3b, v136
	v_exp_f32_e32 v136, v136
	v_cvt_pk_bf16_f32 v70, v135, s0
	ds_write_b16 v133, v70 offset:1584
	v_cvt_pk_bf16_f32 v70, v71, s0
	v_sub_f32_e32 v138, v138, v171
	ds_write_b16 v133, v70 offset:32
	v_cvt_pk_bf16_f32 v70, v144, s0
	v_mul_f32_e32 v138, 0x3fb8aa3b, v138
	ds_write_b16 v133, v70 offset:560
	v_cvt_pk_bf16_f32 v70, v139, s0
	v_exp_f32_e32 v138, v138
	ds_write_b16 v133, v70 offset:1088
	v_cvt_pk_bf16_f32 v70, v136, s0
	ds_write_b16 v133, v70 offset:1616
	v_cvt_pk_bf16_f32 v70, v81, s0
	v_sub_f32_e32 v140, v140, v171
	ds_write_b16 v133, v70 offset:64
	v_cvt_pk_bf16_f32 v70, v148, s0
	v_mul_f32_e32 v140, 0x3fb8aa3b, v140
	ds_write_b16 v133, v70 offset:592
	v_cvt_pk_bf16_f32 v70, v142, s0
	v_exp_f32_e32 v140, v140
	ds_write_b16 v133, v70 offset:1120
	v_cvt_pk_bf16_f32 v70, v138, s0
	ds_write_b16 v133, v70 offset:1648
	v_cvt_pk_bf16_f32 v70, v82, s0
	v_sub_f32_e32 v143, v143, v171
	ds_write_b16 v133, v70 offset:96
	v_cvt_pk_bf16_f32 v70, v152, s0
	v_mul_f32_e32 v143, 0x3fb8aa3b, v143
	ds_write_b16 v133, v70 offset:624
	v_cvt_pk_bf16_f32 v70, v145, s0
	v_exp_f32_e32 v143, v143
	ds_write_b16 v133, v70 offset:1152
	v_cvt_pk_bf16_f32 v70, v140, s0
	ds_write_b16 v133, v70 offset:1680
	v_cvt_pk_bf16_f32 v70, v83, s0
	v_sub_f32_e32 v146, v146, v171
	ds_write_b16 v133, v70 offset:128
	v_cvt_pk_bf16_f32 v70, v157, s0
	v_mul_f32_e32 v146, 0x3fb8aa3b, v146
	ds_write_b16 v133, v70 offset:656
	v_cvt_pk_bf16_f32 v70, v149, s0
	v_exp_f32_e32 v146, v146
	ds_write_b16 v133, v70 offset:1184
	v_cvt_pk_bf16_f32 v70, v143, s0
	ds_write_b16 v133, v70 offset:1712
	v_cvt_pk_bf16_f32 v70, v84, s0
	v_sub_f32_e32 v150, v150, v171
	ds_write_b16 v133, v70 offset:160
	v_cvt_pk_bf16_f32 v70, v160, s0
	v_mul_f32_e32 v150, 0x3fb8aa3b, v150
	ds_write_b16 v133, v70 offset:688
	v_cvt_pk_bf16_f32 v70, v153, s0
	v_exp_f32_e32 v150, v150
	ds_write_b16 v133, v70 offset:1216
	v_cvt_pk_bf16_f32 v70, v146, s0
	ds_write_b16 v133, v70 offset:1744
	v_cvt_pk_bf16_f32 v70, v85, s0
	v_sub_f32_e32 v154, v154, v171
	ds_write_b16 v133, v70 offset:192
	v_cvt_pk_bf16_f32 v70, v161, s0
	v_mul_f32_e32 v154, 0x3fb8aa3b, v154
	ds_write_b16 v133, v70 offset:720
	v_cvt_pk_bf16_f32 v70, v158, s0
	v_exp_f32_e32 v154, v154
	ds_write_b16 v133, v70 offset:1248
	v_cvt_pk_bf16_f32 v70, v150, s0
	ds_write_b16 v133, v70 offset:1776
	v_cvt_pk_bf16_f32 v70, v86, s0
	v_sub_f32_e32 v88, v88, v171
	ds_write_b16 v133, v70 offset:224
	v_cvt_pk_bf16_f32 v70, v163, s0
	v_mul_f32_e32 v88, 0x3fb8aa3b, v88
	ds_write_b16 v133, v70 offset:752
	v_cvt_pk_bf16_f32 v70, v162, s0
	v_exp_f32_e32 v88, v88
	ds_write_b16 v133, v70 offset:1280
	v_cvt_pk_bf16_f32 v70, v154, s0
	ds_write_b16 v133, v70 offset:1808
	v_cvt_pk_bf16_f32 v70, v87, s0
	v_sub_f32_e32 v73, v73, v171
	ds_write_b16 v133, v70 offset:256
	v_cvt_pk_bf16_f32 v70, v90, s0
	v_mul_f32_e32 v73, 0x3fb8aa3b, v73
	ds_write_b16 v133, v70 offset:784
	v_cvt_pk_bf16_f32 v70, v89, s0
	v_exp_f32_e32 v73, v73
	ds_write_b16 v133, v70 offset:1312
	v_cvt_pk_bf16_f32 v70, v88, s0
	ds_write_b16 v133, v70 offset:1840
	v_cvt_pk_bf16_f32 v70, v92, s0
	v_sub_f32_e32 v74, v74, v171
	ds_write_b16 v133, v70 offset:288
	v_cvt_pk_bf16_f32 v70, v79, s0
	v_mul_f32_e32 v74, 0x3fb8aa3b, v74
	ds_write_b16 v133, v70 offset:816
	v_cvt_pk_bf16_f32 v70, v75, s0
	v_exp_f32_e32 v74, v74
	ds_write_b16 v133, v70 offset:1344
	v_cvt_pk_bf16_f32 v70, v73, s0
	v_add_f32_e32 v172, 0, v135
	ds_write_b16 v133, v70 offset:1872
	v_cvt_pk_bf16_f32 v70, v94, s0
	v_add_f32_e32 v172, v136, v172
	v_sub_f32_e32 v76, v76, v171
	ds_write_b16 v133, v70 offset:320
	v_cvt_pk_bf16_f32 v70, v93, s0
	v_add_f32_e32 v172, v138, v172
	v_mul_f32_e32 v76, 0x3fb8aa3b, v76
	ds_write_b16 v133, v70 offset:848
	v_cvt_pk_bf16_f32 v70, v77, s0
	v_add_f32_e32 v172, v140, v172
	v_exp_f32_e32 v76, v76
	ds_write_b16 v133, v70 offset:1376
	v_cvt_pk_bf16_f32 v70, v74, s0
	v_add_f32_e32 v172, v143, v172
	ds_write_b16 v133, v70 offset:1904
	v_cvt_pk_bf16_f32 v70, v147, s0
	v_add_f32_e32 v172, v146, v172
	v_sub_f32_e32 v78, v78, v171
; #define MFMA16(a, b, c) __builtin_amdgcn_mfma_f32_16x16x32_bf16(a, b, c, 0, 0, 0)
; __device__ __forceinline__ void attn_phase(const Params& p, int j, u16* Q, const u16* K, const u16* Vt) {
;     ...
;       s_ = row_sum(s_);
;       inv[jj] = 1.f / s_;
;     }
;     _Pragma("unroll") for (int t = 0; t < 16; ++t) _Pragma("unroll") for (int jj = 0; jj < 4; ++jj)
;       P[(fq * 4 + jj) * 264 + t * 16 + fr] = f2b(sc[t][jj]);
;     f32x4 oc[4];
;     _Pragma("unroll") for (int nd = 0; nd < 4; ++nd) oc[nd] = (f32x4){0.f, 0.f, 0.f, 0.f};
;     auto pv = [&](int bt, const bf16x8 (&vf)[2][4]) {
;       _Pragma("unroll") for (int k2 = 0; k2 < 2; ++k2) {
;         bf16x8 pa = *reinterpret_cast<const bf16x8*>(P + fr * 264 + (bt * 2 + k2) * 32 + fq * 8);
;         _Pragma("unroll") for (int nd = 0; nd < 4; ++nd) oc[nd] = MFMA16(pa, vf[k2][nd], oc[nd]);
;       }
;     };
;     pv(0, vfA);
;     load_v(2, vfA);
;     pv(1, vfB);
;     load_v(3, vfB);
;     pv(2, vfA);
	ds_write_b16 v133, v70 offset:352
	v_cvt_pk_bf16_f32 v70, v95, s0
	v_add_f32_e32 v172, v150, v172
	v_mul_f32_e32 v78, 0x3fb8aa3b, v78
	ds_write_b16 v133, v70 offset:880
	v_cvt_pk_bf16_f32 v70, v91, s0
	v_add_f32_e32 v172, v154, v172
	v_exp_f32_e32 v78, v78
	v_sub_f32_e32 v66, v66, v171
	ds_write_b16 v133, v70 offset:1408
	v_cvt_pk_bf16_f32 v70, v76, s0
	v_add_f32_e32 v172, v88, v172
	v_mul_f32_e32 v66, 0x3fb8aa3b, v66
	v_sub_f32_e32 v68, v68, v171
	ds_write_b16 v133, v70 offset:1936
	v_cvt_pk_bf16_f32 v70, v151, s0
	v_add_f32_e32 v172, v73, v172
	v_exp_f32_e32 v173, v66
	v_mul_f32_e32 v68, 0x3fb8aa3b, v68
	ds_write_b16 v133, v70 offset:384
	v_cvt_pk_bf16_f32 v70, v164, s0
	v_add_f32_e32 v172, v74, v172
	v_exp_f32_e32 v68, v68
	ds_write_b16 v133, v70 offset:912
	v_cvt_pk_bf16_f32 v70, v80, s0
	v_add_f32_e32 v172, v76, v172
	ds_write_b16 v133, v70 offset:1440
	v_cvt_pk_bf16_f32 v70, v78, s0
	v_add_f32_e32 v172, v78, v172
	v_sub_f32_e32 v69, v69, v171
	ds_write_b16 v133, v70 offset:1968
	v_cvt_pk_bf16_f32 v70, v155, s0
	v_add_f32_e32 v66, v173, v172
	v_mul_f32_e32 v69, 0x3fb8aa3b, v69
	ds_write_b16 v133, v70 offset:416
	v_cvt_pk_bf16_f32 v70, v165, s0
	v_add_f32_e32 v66, v68, v66
	v_exp_f32_e32 v69, v69
	ds_write_b16 v133, v70 offset:944
	v_cvt_pk_bf16_f32 v70, v170, s0
	v_cvt_pk_bf16_f32 v68, v68, s0
	ds_write_b16 v133, v70 offset:1472
	v_cvt_pk_bf16_f32 v70, v173, s0
	ds_write_b16 v133, v68 offset:2032
	v_cvt_pk_bf16_f32 v68, v159, s0
	ds_write_b16 v133, v70 offset:2000
	v_cvt_pk_bf16_f32 v70, v156, s0
	ds_write_b16 v133, v68 offset:480
	v_cvt_pk_bf16_f32 v68, v167, s0
	ds_write_b16 v133, v70 offset:448
	v_cvt_pk_bf16_f32 v70, v166, s0
	ds_write_b16 v133, v68 offset:1008
	v_cvt_pk_bf16_f32 v68, v168, s0
	ds_write_b16 v133, v70 offset:976
	v_cvt_pk_bf16_f32 v70, v169, s0
	ds_write_b16 v133, v68 offset:1536
	v_cvt_pk_bf16_f32 v68, v69, s0
	ds_write_b16 v133, v70 offset:1504
	ds_write_b16 v133, v68 offset:2064
	v_add_f32_e32 v66, v69, v66
	ds_read_b128 v[68:71], v128
	ds_read_b128 v[86:89], v128 offset:128
	s_waitcnt vmcnt(15) lgkmcnt(1)
	v_mfma_f32_16x16x32_bf16 v[8:11], v[68:71], v[8:11], 0
	v_add_f32_dpp v66, v66, v66 quad_perm:[1,0,3,2] row_mask:0xf bank_mask:0xf bound_ctrl:1
	s_waitcnt vmcnt(14)
	v_mfma_f32_16x16x32_bf16 v[12:15], v[68:71], v[12:15], 0
	v_add_f32_dpp v66, v66, v66 quad_perm:[2,3,0,1] row_mask:0xf bank_mask:0xf bound_ctrl:1
	s_waitcnt vmcnt(13)
	v_mfma_f32_16x16x32_bf16 v[16:19], v[68:71], v[16:19], 0
	v_add_f32_dpp v66, v66, v66 row_half_mirror row_mask:0xf bank_mask:0xf bound_ctrl:1
	s_waitcnt vmcnt(12)
	v_mfma_f32_16x16x32_bf16 v[20:23], v[68:71], v[20:23], 0
	ds_read_b128 v[68:71], v128 offset:64
	v_add_f32_dpp v66, v66, v66 row_ror:8 row_mask:0xf bank_mask:0xf bound_ctrl:1
	v_div_scale_f32 v171, s[18:19], v66, v66, 1.0
	s_waitcnt vmcnt(11) lgkmcnt(0)
	v_mfma_f32_16x16x32_bf16 v[8:11], v[68:71], v[24:27], v[8:11]
	v_add_u32_e32 v24, 0xa1000, v72
	global_load_dwordx4 v[24:27], v24, s[30:31]
	v_rcp_f32_e32 v172, v171
	s_waitcnt vmcnt(10)
	v_mfma_f32_16x16x32_bf16 v[32:35], v[68:71], v[32:35], v[16:19]
	v_fma_f32 v174, -v171, v172, 1.0
	s_waitcnt vmcnt(8)
	v_mfma_f32_16x16x32_bf16 v[0:3], v[86:89], v[0:3], v[8:11]
	v_add_u32_e32 v16, 0x80000, v72
	v_fmac_f32_e32 v172, v174, v172
	v_div_scale_f32 v174, vcc, 1.0, v66, 1.0
	s_waitcnt vmcnt(7)
	v_mfma_f32_16x16x32_bf16 v[8:11], v[86:89], v[40:43], v[32:35]
	v_mul_f32_e32 v175, v174, v172
	v_fma_f32 v176, -v171, v175, v174
	v_fmac_f32_e32 v175, v176, v172
	ds_read_b128 v[32:35], v128 offset:192
	v_mfma_f32_16x16x32_bf16 v[12:15], v[68:71], v[28:31], v[12:15]
	v_add_u32_e32 v28, 0xa1800, v72
	global_load_dwordx4 v[28:31], v28, s[30:31]
	v_fma_f32 v171, -v171, v175, v174
	v_mfma_f32_16x16x32_bf16 v[36:39], v[68:71], v[36:39], v[20:23]
	global_load_dwordx4 v[68:71], v16, s[30:31]
	v_div_fmas_f32 v171, v171, v172, v175
	v_div_fixup_f32 v66, v171, v66, 1.0
	s_waitcnt vmcnt(8)
	v_mfma_f32_16x16x32_bf16 v[4:7], v[86:89], v[4:7], v[12:15]
	s_waitcnt vmcnt(7)
	v_mfma_f32_16x16x32_bf16 v[12:15], v[86:89], v[44:47], v[36:39]
	ds_read_b128 v[86:89], v128 offset:256
	s_waitcnt vmcnt(6) lgkmcnt(1)
	v_mfma_f32_16x16x32_bf16 v[36:39], v[32:35], v[48:51], v[0:3]
	s_nop 2
	v_add_u32_e32 v0, 0xc0000, v72
	global_load_dwordx4 v[48:51], v0, s[30:31]
	v_add_u32_e32 v16, 0x80800, v72
	v_add_u32_e32 v0, 0xc0800, v72
	global_load_dwordx4 v[74:77], v16, s[30:31]
	s_waitcnt vmcnt(7)
	v_mfma_f32_16x16x32_bf16 v[40:43], v[32:35], v[52:55], v[4:7]
	global_load_dwordx4 v[52:55], v0, s[30:31]
	v_add_u32_e32 v16, 0x81000, v72
	v_add_u32_e32 v0, 0xc1000, v72
	global_load_dwordx4 v[78:81], v16, s[30:31]
	s_waitcnt vmcnt(8)
; #define MFMA16(a, b, c) __builtin_amdgcn_mfma_f32_16x16x32_bf16(a, b, c, 0, 0, 0)
; __device__ __forceinline__ void attn_phase(const Params& p, int j, u16* Q, const u16* K, const u16* Vt) {
;     ...
;     auto pv = [&](int bt, const bf16x8 (&vf)[2][4]) {
;       _Pragma("unroll") for (int k2 = 0; k2 < 2; ++k2) {
;         bf16x8 pa = *reinterpret_cast<const bf16x8*>(P + fr * 264 + (bt * 2 + k2) * 32 + fq * 8);
;         _Pragma("unroll") for (int nd = 0; nd < 4; ++nd) oc[nd] = MFMA16(pa, vf[k2][nd], oc[nd]);
;       }
;     };
;     pv(0, vfA);
;     load_v(2, vfA);
;     pv(1, vfB);
;     load_v(3, vfB);
;     pv(2, vfA);
;     pv(3, vfB);
;     _Pragma("unroll") for (int nd = 0; nd < 4; ++nd) _Pragma("unroll") for (int jj = 0; jj < 4; ++jj)
;       sto<u16>(Q, ((unsigned)(grow * 64 + cb * 16 + fq * 4 + jj) * 1024u + (unsigned)(h * 64 + nd * 16 + fr)) * 2u, f2b(oc[nd][jj] * inv[jj]));
	v_mfma_f32_16x16x32_bf16 v[44:47], v[32:35], v[56:59], v[8:11]
	global_load_dwordx4 v[56:59], v0, s[30:31]
	v_add_u32_e32 v16, 0x81800, v72
	global_load_dwordx4 v[82:85], v16, s[30:31]
	v_add_u32_e32 v0, 0xc1800, v72
	s_waitcnt vmcnt(9)
	v_mfma_f32_16x16x32_bf16 v[32:35], v[32:35], v[60:63], v[12:15]
	global_load_dwordx4 v[60:63], v0, s[30:31]
	v_add_u32_e32 v16, 0xa0000, v72
	v_add_u32_e32 v0, 0xe0000, v72
	global_load_dwordx4 v[20:23], v16, s[30:31]
	global_load_dwordx4 v[8:11], v0, s[30:31]
	v_add_u32_e32 v16, 0xa0800, v72
	global_load_dwordx4 v[16:19], v16, s[30:31]
	v_add_u32_e32 v0, 0xe0800, v72
	global_load_dwordx4 v[12:15], v0, s[30:31]
	v_add_u32_e32 v0, 0xe1000, v72
	global_load_dwordx4 v[4:7], v0, s[30:31]
	v_add_u32_e32 v0, 0xe1800, v72
	global_load_dwordx4 v[0:3], v0, s[30:31]
	s_waitcnt vmcnt(13) lgkmcnt(0)
	v_mfma_f32_16x16x32_bf16 v[36:39], v[86:89], v[68:71], v[36:39]
	ds_read_b128 v[68:71], v128 offset:320
	s_waitcnt vmcnt(7)
	v_mfma_f32_16x16x32_bf16 v[32:35], v[86:89], v[82:85], v[32:35]
	s_waitcnt lgkmcnt(0)
	v_mfma_f32_16x16x32_bf16 v[28:31], v[68:71], v[28:31], v[32:35]
	s_nop 5
	ds_read_b128 v[32:35], v128 offset:384
	v_mfma_f32_16x16x32_bf16 v[40:43], v[86:89], v[74:77], v[40:43]
	v_mfma_f32_16x16x32_bf16 v[44:47], v[86:89], v[78:81], v[44:47]
	s_waitcnt vmcnt(5)
	v_mfma_f32_16x16x32_bf16 v[20:23], v[68:71], v[20:23], v[36:39]
	s_waitcnt vmcnt(3)
	v_mfma_f32_16x16x32_bf16 v[16:19], v[68:71], v[16:19], v[40:43]
	v_mfma_f32_16x16x32_bf16 v[24:27], v[68:71], v[24:27], v[44:47]
	s_waitcnt lgkmcnt(0)
	v_mfma_f32_16x16x32_bf16 v[20:23], v[32:35], v[48:51], v[20:23]
	v_mfma_f32_16x16x32_bf16 v[16:19], v[32:35], v[52:55], v[16:19]
	v_mfma_f32_16x16x32_bf16 v[24:27], v[32:35], v[56:59], v[24:27]
	v_mfma_f32_16x16x32_bf16 v[28:31], v[32:35], v[60:63], v[28:31]
	ds_read_b128 v[32:35], v128 offset:448
	s_waitcnt lgkmcnt(0)
	v_mfma_f32_16x16x32_bf16 v[8:11], v[32:35], v[8:11], v[20:23]
	s_nop 7
	v_mul_f32_e32 v8, v64, v8
	s_waitcnt vmcnt(2)
	v_mfma_f32_16x16x32_bf16 v[12:15], v[32:35], v[12:15], v[16:19]
	v_cvt_pk_bf16_f32 v8, v8, s0
	v_mul_f32_e32 v9, v65, v9
	v_cvt_pk_bf16_f32 v9, v9, s0
	v_or_b32_e32 v16, v134, v119
	v_or_b32_e32 v17, s3, v112
	v_lshlrev_b32_e32 v16, 11, v16
	v_lshlrev_b32_e32 v17, 1, v17
	v_or_b32_e32 v18, v16, v17
	global_store_short v18, v8, s[54:55]
	v_or_b32_e32 v8, 0x800, v16
	v_or_b32_e32 v18, v8, v17
	global_store_short v18, v9, s[54:55]
	v_or_b32_e32 v9, 0x1000, v16
	v_mul_f32_e32 v10, v67, v10
	v_or_b32_e32 v18, v9, v17
	v_cvt_pk_bf16_f32 v10, v10, s0
	global_store_short v18, v10, s[54:55]
	v_or_b32_e32 v10, 0x1800, v16
	v_mul_f32_e32 v11, v66, v11
	v_or_b32_e32 v18, v10, v17
	v_cvt_pk_bf16_f32 v11, v11, s0
	global_store_short v18, v11, s[54:55]
	v_or_b32_e32 v11, 32, v17
	v_mul_f32_e32 v12, v64, v12
	v_or_b32_e32 v18, v16, v11
	v_cvt_pk_bf16_f32 v12, v12, s0
	v_mul_f32_e32 v13, v65, v13
	global_store_short v18, v12, s[54:55]
	v_or_b32_e32 v12, v8, v11
	v_cvt_pk_bf16_f32 v13, v13, s0
	s_waitcnt vmcnt(6)
	v_mfma_f32_16x16x32_bf16 v[4:7], v[32:35], v[4:7], v[24:27]
	global_store_short v12, v13, s[54:55]
	v_mul_f32_e32 v13, v67, v14
	v_or_b32_e32 v12, v9, v11
	v_cvt_pk_bf16_f32 v13, v13, s0
	global_store_short v12, v13, s[54:55]
	v_mul_f32_e32 v12, v66, v15
	v_or_b32_e32 v11, v10, v11
	v_cvt_pk_bf16_f32 v12, v12, s0
	global_store_short v11, v12, s[54:55]
	v_or_b32_e32 v11, 64, v17
	v_mul_f32_e32 v4, v64, v4
	v_or_b32_e32 v12, v16, v11
	v_cvt_pk_bf16_f32 v4, v4, s0
	v_mul_f32_e32 v5, v65, v5
	global_store_short v12, v4, s[54:55]
	v_or_b32_e32 v4, v8, v11
	v_cvt_pk_bf16_f32 v5, v5, s0
	s_waitcnt vmcnt(9)
	v_mfma_f32_16x16x32_bf16 v[0:3], v[32:35], v[0:3], v[28:31]
	global_store_short v4, v5, s[54:55]
	v_mul_f32_e32 v5, v67, v6
	v_or_b32_e32 v4, v9, v11
	v_cvt_pk_bf16_f32 v5, v5, s0
	global_store_short v4, v5, s[54:55]
	v_mul_f32_e32 v5, v66, v7
	v_or_b32_e32 v4, v10, v11
	v_cvt_pk_bf16_f32 v5, v5, s0
	global_store_short v4, v5, s[54:55]
	v_or_b32_e32 v4, 0x60, v17
	v_mul_f32_e32 v0, v64, v0
	v_or_b32_e32 v5, v16, v4
	v_cvt_pk_bf16_f32 v0, v0, s0
	v_mul_f32_e32 v1, v65, v1
	global_store_short v5, v0, s[54:55]
	v_or_b32_e32 v0, v8, v4
	v_cvt_pk_bf16_f32 v1, v1, s0
	global_store_short v0, v1, s[54:55]
	v_mul_f32_e32 v1, v67, v2
	v_or_b32_e32 v0, v9, v4
	v_cvt_pk_bf16_f32 v1, v1, s0
	global_store_short v0, v1, s[54:55]
	v_mul_f32_e32 v1, v66, v3
	v_or_b32_e32 v0, v10, v4
	v_cvt_pk_bf16_f32 v1, v1, s0
	global_store_short v0, v1, s[54:55]
	s_cbranch_scc0 .LBB0_584
